# candG + P7 peer_coef row loop: next row's 7 first-level loads prefetched (copy-based) behind this row's scale gathers, counted waits
# baseline (speedup 1.0000x reference)
; __device__ __forceinline__ float bf_lo(unsigned w) { return __uint_as_float(w << 16); }
; __device__ __forceinline__ float bf_hi(unsigned w) { return __uint_as_float(w & 0xffff0000u); }
; __device__ __forceinline__ float gelu_erf(float x) { return 0.5f * x * (1.0f + erff(x * 0.70710678118654752f)); }
; __device__ __forceinline__ void peer_coef(const Args& a, const int widx, const int nwtot, const int row_lo, const int row_hi) {
;     ...
;     for (int row = row_lo + widx; row < row_hi; row += nwtot) {
;         const unsigned* kp = (const unsigned*)(ws + WS_PEERK) + (size_t)row * 256 + 4 * l5;
;         const unsigned* pd = (const unsigned*)(ws + WS_PD) + (size_t)row * 512 + half * 256 + 2 * l5;
;         const u32x4 ids = *(const u32x4*)kp;
;         const f32x4 g = *(const f32x4*)(kp + 128);
;         f32x4 d = {0.f, 0.f, 0.f, 0.f};
; #pragma unroll
;         for (int sl = 0; sl < 4; ++sl) { const u32x2 pw = *(const u32x2*)(pd + sl * 64); d = d + (f32x4){bf_lo(pw.x), bf_hi(pw.x), bf_lo(pw.y), bf_hi(pw.y)}; }
;         const f32x2 s0 = SC[ids.x], s1 = SC[ids.y], s2 = SC[ids.z], s3 = SC[ids.w];
;         const float rs2 = rsqrtf(rowss[row] * (1.0f / DM) + EPS);
; #pragma unroll
;         for (int c = 0; c < 4; ++c) d[c] += __shfl_xor(d[c], 32);
;         f32x4 cf;
;         cf[0] = g[0] * gelu_erf(d[0] * rs2 * s0[0]) * s0[1]; cf[1] = g[1] * gelu_erf(d[1] * rs2 * s1[0]) * s1[1];
.LBB0_1511:
	s_andn2_b64 vcc, exec, s[0:1]
	s_cbranch_vccnz .LBB0_1534
	s_lshl_b32 s0, s86, 2
	s_or_b32 s4, s42, s0
	s_cmpk_gt_i32 s4, 0x3fff
	s_cbranch_scc1 .LBB0_1534
	s_lshl_b32 s6, s3, 2
	s_add_u32 s8, s24, 0x4ca6000
	s_addc_u32 s9, s25, 0
	s_ashr_i32 s5, s4, 31
	s_lshl_b64 s[0:1], s[4:5], 2
	s_add_u32 s0, s24, s0
	s_addc_u32 s1, s25, s1
	v_mbcnt_lo_u32_b32 v1, -1, 0
	s_add_u32 s10, s0, 0x4000
	v_mbcnt_hi_u32_b32 v1, -1, v1
	s_addc_u32 s11, s1, 0
	s_ashr_i32 s7, s6, 31
	s_waitcnt vmcnt(0)
	v_and_b32_e32 v3, 64, v1
	s_lshl_b64 s[12:13], s[6:7], 2
	s_lshl_b64 s[0:1], s[4:5], 9
	v_xor_b32_e32 v2, 32, v1
	v_add_u32_e32 v3, 64, v3
	v_and_b32_e32 v5, 31, v0
	s_add_u32 s0, s24, s0
	v_cmp_lt_i32_e32 vcc, v2, v3
	v_lshlrev_b32_e32 v6, 4, v5
	v_mov_b32_e32 v7, 0
	s_addc_u32 s1, s25, s1
	v_cndmask_b32_e32 v1, v1, v2, vcc
	v_lshl_add_u64 v[2:3], s[0:1], 0, v[6:7]
	s_mov_b64 s[0:1], 0x20846000
	v_lshl_add_u64 v[8:9], v[2:3], 0, s[0:1]
	s_lshl_b64 s[14:15], s[6:7], 9
	s_lshl_b64 s[0:1], s[4:5], 10
	s_add_u32 s0, s24, s0
	s_addc_u32 s1, s25, s1
	v_bfe_u32 v4, v0, 5, 1
	v_lshl_add_u64 v[2:3], s[0:1], 0, v[6:7]
	s_mov_b64 s[0:1], 0x1b346200
	v_lshl_add_u64 v[10:11], v[2:3], 0, s[0:1]
	s_lshl_b64 s[0:1], s[4:5], 11
	v_lshlrev_b32_e32 v2, 10, v4
	v_lshlrev_b32_e32 v3, 3, v5
	v_or3_b32 v2, s0, v2, v3
	v_mov_b32_e32 v3, s1
	v_lshl_add_u64 v[2:3], s[24:25], 0, v[2:3]
	s_mov_b64 s[0:1], 0x1c446200
	v_lshlrev_b32_e32 v1, 2, v1
	v_cmp_eq_u32_e32 vcc, 0, v4
	s_lshl_b64 s[16:17], s[6:7], 10
	v_lshl_add_u64 v[12:13], v[2:3], 0, s[0:1]
	s_lshl_b64 s[18:19], s[6:7], 11
	v_mov_b32_e32 v26, 0x358637bd
	s_mov_b32 s2, 0x800000
	s_mov_b32 s5, 0x378e98ab
	s_mov_b32 s7, 0x3b7cd369
	s_mov_b32 s22, 0xbcc618b2
	s_mov_b32 s23, 0x3dda74e4
	s_mov_b32 s33, 0x3f228afd
	s_mov_b32 s34, 0x3e03c728
	s_mov_b32 s35, 0xbfb8aa3b
	s_mov_b32 s36, 0x42ce8ed0
	s_mov_b32 s37, 0xc2b17218
	v_mov_b32_e32 v27, 0x3ba10414
	s_brev_b32 s38, -2
	v_mov_b32_e32 v28, 0xb9c68948
	v_mov_b32_e32 v29, 0x7f800000
	global_load_dwordx4 v[200:203], v[10:11], off offset:-512
	global_load_dwordx2 v[204:205], v[12:13], off offset:-512
	global_load_dwordx2 v[206:207], v[12:13], off offset:-256
	global_load_dwordx2 v[208:209], v[12:13], off
	global_load_dwordx2 v[210:211], v[12:13], off offset:256
	global_load_dword v212, v7, s[10:11]
	global_load_dwordx4 v[214:217], v[10:11], off
	s_waitcnt vmcnt(0)
	s_branch .Lpc_copy
.LBB0_1514:
	s_or_b64 exec, exec, s[0:1]
	s_add_i32 s4, s4, s6
	s_add_u32 s10, s10, s12
	s_addc_u32 s11, s11, s13
	v_lshl_add_u64 v[8:9], v[8:9], 0, s[14:15]
	v_lshl_add_u64 v[10:11], v[10:11], 0, s[16:17]
	s_cmpk_gt_i32 s4, 0x3fff
	v_lshl_add_u64 v[12:13], v[12:13], 0, s[18:19]
	s_cbranch_scc1 .LBB0_1533
.LBB0_1515:
	s_waitcnt vmcnt(1)
.Lpc_copy:
	v_mov_b64_e32 v[14:15], v[200:201]
	v_mov_b64_e32 v[16:17], v[202:203]
	v_mov_b64_e32 v[22:23], v[204:205]
	v_mov_b64_e32 v[24:25], v[206:207]
	v_mov_b64_e32 v[30:31], v[208:209]
	v_mov_b64_e32 v[32:33], v[210:211]
	v_mov_b32_e32 v42, v212
	v_mov_b64_e32 v[2:3], v[214:215]
	v_mov_b64_e32 v[4:5], v[216:217]
	v_mov_b32_e32 v6, v14
	v_lshl_add_u64 v[34:35], v[6:7], 3, s[8:9]
	v_mov_b32_e32 v6, v15
	v_lshl_add_u64 v[36:37], v[6:7], 3, s[8:9]
	v_mov_b32_e32 v6, v16
	v_lshl_add_u64 v[38:39], v[6:7], 3, s[8:9]
	v_mov_b32_e32 v6, v17
	v_lshl_add_u64 v[40:41], v[6:7], 3, s[8:9]
	global_load_dwordx2 v[20:21], v[34:35], off
	global_load_dwordx2 v[18:19], v[36:37], off
	global_load_dwordx2 v[16:17], v[38:39], off
	global_load_dwordx2 v[14:15], v[40:41], off
	s_add_i32 s0, s4, s6
	s_cmpk_gt_i32 s0, 0x3fff
	s_cselect_b32 s0, 0, s16
	s_cselect_b32 s1, 0, s17
	s_cselect_b32 s30, 0, s18
	s_cselect_b32 s31, 0, s19
	v_lshl_add_u64 v[218:219], v[10:11], 0, s[0:1]
	v_lshl_add_u64 v[220:221], v[12:13], 0, s[30:31]
	s_cselect_b32 s0, 0, s12
	s_cselect_b32 s1, 0, s13
	s_add_u32 s0, s10, s0
	s_addc_u32 s1, s11, s1
	global_load_dwordx4 v[200:203], v[218:219], off offset:-512
	global_load_dwordx2 v[204:205], v[220:221], off offset:-512
	global_load_dwordx2 v[206:207], v[220:221], off offset:-256
	global_load_dwordx2 v[208:209], v[220:221], off
	global_load_dwordx2 v[210:211], v[220:221], off offset:256
	global_load_dword v212, v7, s[0:1]
	global_load_dwordx4 v[214:217], v[218:219], off
	v_lshlrev_b32_e32 v34, 16, v22
	v_and_b32_e32 v35, 0xffff0000, v22
	v_lshlrev_b32_e32 v22, 16, v23
	v_and_b32_e32 v23, 0xffff0000, v23
	v_pk_add_f32 v[34:35], v[34:35], 0 op_sel_hi:[1,0]
	v_pk_add_f32 v[22:23], v[22:23], 0 op_sel_hi:[1,0]
	v_lshlrev_b32_e32 v36, 16, v24
	v_and_b32_e32 v37, 0xffff0000, v24
	v_lshlrev_b32_e32 v24, 16, v25
	v_and_b32_e32 v25, 0xffff0000, v25
	v_pk_add_f32 v[22:23], v[22:23], v[24:25]
	v_pk_add_f32 v[24:25], v[34:35], v[36:37]
	v_lshlrev_b32_e32 v34, 16, v30
	v_and_b32_e32 v35, 0xffff0000, v30
	v_lshlrev_b32_e32 v30, 16, v31
	v_and_b32_e32 v31, 0xffff0000, v31
	v_pk_add_f32 v[24:25], v[24:25], v[34:35]
	v_pk_add_f32 v[22:23], v[22:23], v[30:31]
	v_lshlrev_b32_e32 v30, 16, v32
	v_and_b32_e32 v31, 0xffff0000, v32
	v_fmamk_f32 v6, v42, 0x3a800000, v26
	v_pk_add_f32 v[24:25], v[24:25], v[30:31]
	v_mul_f32_e32 v30, 0x4b800000, v6
	v_cmp_gt_f32_e64 s[0:1], s2, v6
	ds_bpermute_b32 v32, v1, v24
	v_and_b32_e32 v31, 0xffff0000, v33
	v_cndmask_b32_e64 v6, v6, v30, s[0:1]
	v_rsq_f32_e32 v6, v6
	v_lshlrev_b32_e32 v30, 16, v33
	v_pk_add_f32 v[22:23], v[22:23], v[30:31]
	s_waitcnt lgkmcnt(0)
	v_add_f32_e32 v24, v24, v32
	v_mul_f32_e32 v31, 0x45800000, v6
	ds_bpermute_b32 v32, v1, v25
	ds_bpermute_b32 v33, v1, v22
	ds_bpermute_b32 v30, v1, v23
	v_cndmask_b32_e64 v31, v6, v31, s[0:1]
	v_mul_f32_e32 v6, v24, v31
	s_waitcnt vmcnt(10)
	v_mul_f32_e32 v6, v20, v6
	v_mul_f32_e32 v20, 0x3f3504f3, v6
	v_cmp_nlt_f32_e64 s[0:1], |v20|, 1.0
	s_and_saveexec_b64 s[30:31], s[0:1]
	s_xor_b64 s[30:31], exec, s[30:31]
	s_cbranch_execz .LBB0_1517
	v_fma_f32 v24, |v20|, s5, v28
	v_fma_f32 v24, |v20|, v24, s7
	v_fma_f32 v24, |v20|, v24, s22
	v_fma_f32 v24, |v20|, v24, s23
	v_fma_f32 v24, |v20|, v24, s33
	v_fma_f32 v24, |v20|, v24, s34
	v_fma_f32 v24, |v20|, v24, |v20|
	v_mul_f32_e32 v34, 0xbfb8aa3b, v24
	v_fma_f32 v35, v24, s35, -v34
	v_rndne_f32_e32 v36, v34
	v_fmac_f32_e32 v35, 0xb2a5705f, v24
	v_sub_f32_e32 v34, v34, v36
	v_add_f32_e32 v34, v34, v35
	v_cvt_i32_f32_e32 v35, v36
	v_exp_f32_e32 v34, v34
	v_cmp_nlt_f32_e64 s[0:1], s36, v24
	v_ldexp_f32 v34, v34, v35
	s_nop 0
	v_cndmask_b32_e64 v34, 0, v34, s[0:1]
	v_cmp_ngt_f32_e64 s[0:1], s37, v24
	s_nop 1
	v_cndmask_b32_e64 v24, v29, v34, s[0:1]
	v_sub_f32_e32 v24, 1.0, v24
; __device__ __forceinline__ float gelu_erf(float x) { return 0.5f * x * (1.0f + erff(x * 0.70710678118654752f)); }
; __device__ __forceinline__ void peer_coef(const Args& a, const int widx, const int nwtot, const int row_lo, const int row_hi) {
;     ...
;         const float rs2 = rsqrtf(rowss[row] * (1.0f / DM) + EPS);
; #pragma unroll
;         for (int c = 0; c < 4; ++c) d[c] += __shfl_xor(d[c], 32);
;         f32x4 cf;
;         cf[0] = g[0] * gelu_erf(d[0] * rs2 * s0[0]) * s0[1]; cf[1] = g[1] * gelu_erf(d[1] * rs2 * s1[0]) * s1[1];
;         cf[2] = g[2] * gelu_erf(d[2] * rs2 * s2[0]) * s2[1]; cf[3] = g[3] * gelu_erf(d[3] * rs2 * s3[0]) * s3[1];
.LBB0_1517:
	s_andn2_saveexec_b64 s[0:1], s[30:31]
	v_mul_f32_e32 v24, v20, v20
	v_fmamk_f32 v34, v24, 0xba1345e1, v27
	v_fmaak_f32 v34, v24, v34, 0xbcdac9b8
	v_fmaak_f32 v34, v24, v34, 0x3de703be
	v_fmaak_f32 v34, v24, v34, 0xbec09330
	v_fmaak_f32 v24, v24, v34, 0x3e0375d0
	v_fma_f32 v24, |v20|, v24, |v20|
	s_or_b64 exec, exec, s[0:1]
	s_waitcnt lgkmcnt(2)
	v_add_f32_e32 v25, v25, v32
	v_mul_f32_e32 v25, v25, v31
	s_waitcnt vmcnt(9)
	v_mul_f32_e32 v18, v18, v25
	v_mul_f32_e32 v25, 0x3f3504f3, v18
	v_cmp_nlt_f32_e64 s[0:1], |v25|, 1.0
	s_and_saveexec_b64 s[30:31], s[0:1]
	s_xor_b64 s[30:31], exec, s[30:31]
	s_cbranch_execz .LBB0_1521
	v_fma_f32 v32, |v25|, s5, v28
	v_fma_f32 v32, |v25|, v32, s7
	v_fma_f32 v32, |v25|, v32, s22
	v_fma_f32 v32, |v25|, v32, s23
	v_fma_f32 v32, |v25|, v32, s33
	v_fma_f32 v32, |v25|, v32, s34
	v_fma_f32 v32, |v25|, v32, |v25|
	v_mul_f32_e32 v34, 0xbfb8aa3b, v32
	v_fma_f32 v35, v32, s35, -v34
	v_rndne_f32_e32 v36, v34
	v_fmac_f32_e32 v35, 0xb2a5705f, v32
	v_sub_f32_e32 v34, v34, v36
	v_add_f32_e32 v34, v34, v35
	v_cvt_i32_f32_e32 v35, v36
	v_exp_f32_e32 v34, v34
	v_cmp_nlt_f32_e64 s[0:1], s36, v32
	v_ldexp_f32 v34, v34, v35
	s_nop 0
	v_cndmask_b32_e64 v34, 0, v34, s[0:1]
	v_cmp_ngt_f32_e64 s[0:1], s37, v32
	s_nop 1
	v_cndmask_b32_e64 v32, v29, v34, s[0:1]
	v_sub_f32_e32 v32, 1.0, v32
.LBB0_1521:
	s_andn2_saveexec_b64 s[0:1], s[30:31]
	v_mul_f32_e32 v32, v25, v25
	v_fmamk_f32 v34, v32, 0xba1345e1, v27
	v_fmaak_f32 v34, v32, v34, 0xbcdac9b8
	v_fmaak_f32 v34, v32, v34, 0x3de703be
	v_fmaak_f32 v34, v32, v34, 0xbec09330
	v_fmaak_f32 v32, v32, v34, 0x3e0375d0
	v_fma_f32 v32, |v25|, v32, |v25|
	s_or_b64 exec, exec, s[0:1]
	s_waitcnt lgkmcnt(1)
	v_add_f32_e32 v22, v22, v33
	v_mul_f32_e32 v22, v22, v31
	s_waitcnt vmcnt(8)
	v_mul_f32_e32 v16, v16, v22
	v_mul_f32_e32 v22, 0x3f3504f3, v16
	v_cmp_nlt_f32_e64 s[0:1], |v22|, 1.0
	s_and_saveexec_b64 s[30:31], s[0:1]
	s_xor_b64 s[30:31], exec, s[30:31]
	s_cbranch_execz .LBB0_1525
	v_fma_f32 v33, |v22|, s5, v28
	v_fma_f32 v33, |v22|, v33, s7
	v_fma_f32 v33, |v22|, v33, s22
	v_fma_f32 v33, |v22|, v33, s23
	v_fma_f32 v33, |v22|, v33, s33
	v_fma_f32 v33, |v22|, v33, s34
	v_fma_f32 v33, |v22|, v33, |v22|
	v_mul_f32_e32 v34, 0xbfb8aa3b, v33
	v_fma_f32 v35, v33, s35, -v34
	v_rndne_f32_e32 v36, v34
	v_fmac_f32_e32 v35, 0xb2a5705f, v33
	v_sub_f32_e32 v34, v34, v36
	v_add_f32_e32 v34, v34, v35
	v_cvt_i32_f32_e32 v35, v36
	v_exp_f32_e32 v34, v34
	v_cmp_nlt_f32_e64 s[0:1], s36, v33
	v_ldexp_f32 v34, v34, v35
	s_nop 0
	v_cndmask_b32_e64 v34, 0, v34, s[0:1]
	v_cmp_ngt_f32_e64 s[0:1], s37, v33
	s_nop 1
	v_cndmask_b32_e64 v33, v29, v34, s[0:1]
	v_sub_f32_e32 v33, 1.0, v33
.LBB0_1525:
	s_andn2_saveexec_b64 s[0:1], s[30:31]
	v_mul_f32_e32 v33, v22, v22
	v_fmamk_f32 v34, v33, 0xba1345e1, v27
	v_fmaak_f32 v34, v33, v34, 0xbcdac9b8
	v_fmaak_f32 v34, v33, v34, 0x3de703be
	v_fmaak_f32 v34, v33, v34, 0xbec09330
	v_fmaak_f32 v33, v33, v34, 0x3e0375d0
	v_fma_f32 v33, |v22|, v33, |v22|
	s_or_b64 exec, exec, s[0:1]
	s_waitcnt lgkmcnt(0)
	v_add_f32_e32 v23, v23, v30
	v_mul_f32_e32 v23, v23, v31
	s_waitcnt vmcnt(7)
	v_mul_f32_e32 v14, v14, v23
	v_mul_f32_e32 v23, 0x3f3504f3, v14
	v_cmp_nlt_f32_e64 s[0:1], |v23|, 1.0
	s_and_saveexec_b64 s[30:31], s[0:1]
	s_xor_b64 s[30:31], exec, s[30:31]
	s_cbranch_execnz .LBB0_1530
	s_andn2_saveexec_b64 s[0:1], s[30:31]
	s_cbranch_execnz .LBB0_1531
